# attention loop rescheduled: QK(jt1) MFMAs overlap max/exp of jt0, PV(jt0) overlaps jt1 softmax, row sums under PV(jt1)
# speedup vs baseline: 1.0207x; 1.0002x over previous
; DEV f32x16 mfma32(bf16x8 a, bf16x8 b, f32x16 c) { return __builtin_amdgcn_mfma_f32_32x32x16_bf16(a, b, c, 0, 0, 0); }
; DEV void attn_item(const Params& p, int item, char* smem) {
;     ...
;   for (int kt = 0; kt < ntile; kt++) {
;     const bf16_t* Kc = Ks + (kt & 1) * (32 * ASTR);
;     const bf16_t* Vc = Vs + (kt & 1) * (64 * VSTR);
;     f32x16 s[2];
; #pragma unroll
;     for (int jt = 0; jt < 2; jt++) {
; #pragma unroll
;       for (int r = 0; r < 16; r++) s[jt][r] = 0.f;
; #pragma unroll
;       for (int ks = 0; ks < 6; ks++) {
;         bf16x8 kf = *(const bf16x8*)(Kc + c31 * ASTR + ks * 16 + hf * 8);
;         s[jt] = mfma32(kf, qf[jt][ks], s[jt]);
;       }
;     }
; #pragma unroll
;     for (int jt = 0; jt < 2; jt++) {
;       float m0 = fmaxf(fmaxf(s[jt][0], s[jt][1]), fmaxf(s[jt][2], s[jt][3]));
;       float m1 = fmaxf(fmaxf(s[jt][4], s[jt][5]), fmaxf(s[jt][6], s[jt][7]));
;       float m2 = fmaxf(fmaxf(s[jt][8], s[jt][9]), fmaxf(s[jt][10], s[jt][11]));
;       float m3 = fmaxf(fmaxf(s[jt][12], s[jt][13]), fmaxf(s[jt][14], s[jt][15]));
;       const float mx = fmaxf(fmaxf(m0, m1), fmaxf(m2, m3));
;       if (__any(mx > mrun[jt])) {
;         const float mxa = fmaxf(mx, __shfl_xor(mx, 32));
;         const float mnew = fmaxf(mrun[jt], mxa);
;         const float alpha = __builtin_amdgcn_exp2f(mrun[jt] - mnew);
;         mrun[jt] = mnew;
;         lrun[jt] *= alpha;
; #pragma unroll
;         for (int dt = 0; dt < 2; dt++)
; #pragma unroll
;           for (int r = 0; r < 16; r++) o[dt][jt][r] *= alpha;
;       }
;       const float mcur = mrun[jt];
;       float pv[16];
; #pragma unroll
;       for (int r = 0; r < 16; r++) pv[r] = __builtin_amdgcn_exp2f(s[jt][r] - mcur);
;       lrun[jt] += (((pv[0] + pv[1]) + (pv[2] + pv[3])) + ((pv[4] + pv[5]) + (pv[6] + pv[7]))) +
;                   (((pv[8] + pv[9]) + (pv[10] + pv[11])) + ((pv[12] + pv[13]) + (pv[14] + pv[15])));
.LBB0_752:
	s_or_b64 exec, exec, s[8:9]
	v_add_f32_e32 v4, v80, v81
	v_add_f32_e32 v5, v82, v83
	v_add_f32_e32 v4, v4, v5
	v_add_f32_e32 v5, v84, v85
	v_add_f32_e32 v6, v86, v111
	v_add_f32_e32 v5, v5, v6
	v_add_f32_e32 v4, v4, v5
	v_add_f32_e32 v5, v87, v88
	v_add_f32_e32 v6, v89, v90
	v_add_f32_e32 v5, v5, v6
	v_add_f32_e32 v6, v91, v92
	v_add_f32_e32 v2, v2, v3
	v_add_f32_e32 v2, v6, v2
	v_add_f32_e32 v2, v5, v2
	v_add_f32_e32 v2, v4, v2
	v_add_f32_e32 v184, v184, v2
	s_mul_i32 s8, s14, 0x1600
	v_add_u32_e32 v0, s8, v186
	v_add_u32_e32 v0, 0x3400, v0
	ds_write2_b64 v0, v[160:161], v[162:163] offset1:1
	s_waitcnt lgkmcnt(0)
	s_barrier
	global_load_dwordx4 v[168:171], v[182:183], off
	global_load_dwordx4 v[164:167], v[180:181], off
	global_load_dwordx4 v[160:163], v[178:179], off
	s_mov_b64 s[8:9], 0x1800
	v_lshl_add_u64 v[178:179], v[178:179], 0, 64
	v_lshl_add_u64 v[180:181], v[180:181], 0, s[8:9]
	v_lshl_add_u64 v[182:183], v[182:183], 0, s[8:9]
	s_cmp_eq_u32 s13, s12
	s_cbranch_scc1 .LBB0_759
.LBB0_753:
	s_and_b32 s11, s12, 1
	s_mul_i32 s10, s11, 0x1a00
	v_add_u32_e32 v0, s10, v187
	ds_read_b128 v[2:5], v0
	ds_read_b128 v[6:9], v0 offset:32
	ds_read_b128 v[10:13], v0 offset:64
	ds_read_b128 v[240:243], v0 offset:96
	ds_read_b128 v[244:247], v0 offset:128
	ds_read_b128 v[236:239], v0 offset:160
	s_waitcnt lgkmcnt(5)
	v_mfma_f32_32x32x16_bf16 v[96:111], v[2:5], v[156:159], v[196:211]
	s_waitcnt lgkmcnt(4)
	v_mfma_f32_32x32x16_bf16 v[96:111], v[6:9], v[152:155], v[96:111]
	s_waitcnt lgkmcnt(3)
	v_mfma_f32_32x32x16_bf16 v[96:111], v[10:13], v[148:151], v[96:111]
	s_waitcnt lgkmcnt(2)
	v_mfma_f32_32x32x16_bf16 v[96:111], v[240:243], v[144:147], v[96:111]
	s_waitcnt lgkmcnt(1)
	v_mfma_f32_32x32x16_bf16 v[96:111], v[244:247], v[140:143], v[96:111]
	s_waitcnt lgkmcnt(0)
	v_mfma_f32_32x32x16_bf16 v[96:111], v[236:239], v[136:139], v[96:111]
	v_mfma_f32_32x32x16_bf16 v[80:95], v[2:5], v[132:135], v[220:235]
	v_mfma_f32_32x32x16_bf16 v[80:95], v[6:9], v[128:131], v[80:95]
	v_mfma_f32_32x32x16_bf16 v[80:95], v[10:13], v[112:115], v[80:95]
	s_nop 4
	v_max3_f32 v0, v96, v97, v98
	v_max3_f32 v2, v99, v100, v101
	v_max3_f32 v3, v102, v103, v104
	v_max3_f32 v4, v105, v106, v107
	v_max3_f32 v5, v108, v109, v110
	v_max3_f32 v0, v0, v2, v111
	v_max3_f32 v3, v3, v4, v5
	v_max_f32_e32 v0, v0, v3
	v_cmp_gt_f32_e32 vcc, v0, v212
	s_cbranch_vccz .LBB0_755
	v_mbcnt_hi_u32_b32 v2, -1, v215
	v_and_b32_e32 v4, 64, v2
	v_xor_b32_e32 v3, 32, v2
	v_add_u32_e32 v4, 64, v4
	v_cmp_lt_i32_e32 vcc, v3, v4
	s_nop 1
	v_cndmask_b32_e32 v2, v2, v3, vcc
	v_lshlrev_b32_e32 v2, 2, v2
	ds_bpermute_b32 v2, v2, v0
	s_waitcnt lgkmcnt(0)
	v_max_f32_e32 v2, v0, v2
	v_exp_f32_e64 v0, -v2
	v_add_f32_e32 v185, v185, v2
	v_mov_b32_e32 v212, 0x41000000
	v_sub_f32_e32 v96, v96, v2
	v_sub_f32_e32 v97, v97, v2
	v_sub_f32_e32 v98, v98, v2
	v_sub_f32_e32 v99, v99, v2
	v_sub_f32_e32 v100, v100, v2
	v_sub_f32_e32 v101, v101, v2
	v_sub_f32_e32 v102, v102, v2
	v_sub_f32_e32 v103, v103, v2
	v_sub_f32_e32 v104, v104, v2
	v_sub_f32_e32 v105, v105, v2
	v_sub_f32_e32 v106, v106, v2
	v_sub_f32_e32 v107, v107, v2
	v_sub_f32_e32 v108, v108, v2
	v_sub_f32_e32 v109, v109, v2
	v_sub_f32_e32 v110, v110, v2
	v_sub_f32_e32 v111, v111, v2
	v_sub_f32_e32 v196, v196, v2
	v_sub_f32_e32 v197, v197, v2
	v_sub_f32_e32 v198, v198, v2
	v_sub_f32_e32 v199, v199, v2
	v_sub_f32_e32 v200, v200, v2
	v_sub_f32_e32 v201, v201, v2
	v_sub_f32_e32 v202, v202, v2
	v_sub_f32_e32 v203, v203, v2
	v_sub_f32_e32 v204, v204, v2
	v_sub_f32_e32 v205, v205, v2
	v_sub_f32_e32 v206, v206, v2
	v_sub_f32_e32 v207, v207, v2
	v_sub_f32_e32 v208, v208, v2
	v_sub_f32_e32 v209, v209, v2
	v_sub_f32_e32 v210, v210, v2
	v_sub_f32_e32 v211, v211, v2
	v_mul_f32_e32 v14, v14, v0
	v_pk_mul_f32 v[46:47], v[46:47], v[0:1] op_sel_hi:[1,0]
	v_pk_mul_f32 v[44:45], v[44:45], v[0:1] op_sel_hi:[1,0]
	v_pk_mul_f32 v[42:43], v[42:43], v[0:1] op_sel_hi:[1,0]
	v_pk_mul_f32 v[40:41], v[40:41], v[0:1] op_sel_hi:[1,0]
	v_pk_mul_f32 v[38:39], v[38:39], v[0:1] op_sel_hi:[1,0]
	v_pk_mul_f32 v[36:37], v[36:37], v[0:1] op_sel_hi:[1,0]
	v_pk_mul_f32 v[34:35], v[34:35], v[0:1] op_sel_hi:[1,0]
	v_pk_mul_f32 v[32:33], v[32:33], v[0:1] op_sel_hi:[1,0]
	v_pk_mul_f32 v[30:31], v[30:31], v[0:1] op_sel_hi:[1,0]
	v_pk_mul_f32 v[28:29], v[28:29], v[0:1] op_sel_hi:[1,0]
	v_pk_mul_f32 v[26:27], v[26:27], v[0:1] op_sel_hi:[1,0]
	v_pk_mul_f32 v[24:25], v[24:25], v[0:1] op_sel_hi:[1,0]
	v_pk_mul_f32 v[22:23], v[22:23], v[0:1] op_sel_hi:[1,0]
	v_pk_mul_f32 v[20:21], v[20:21], v[0:1] op_sel_hi:[1,0]
	v_pk_mul_f32 v[18:19], v[18:19], v[0:1] op_sel_hi:[1,0]
	v_pk_mul_f32 v[16:17], v[16:17], v[0:1] op_sel_hi:[1,0]
; DEV unsigned pack2(float a, float b) { f32x2 v = {a, b}; return __builtin_bit_cast(unsigned, __builtin_convertvector(v, bf2_t)); }
; DEV f32x16 mfma32(bf16x8 a, bf16x8 b, f32x16 c) { return __builtin_amdgcn_mfma_f32_32x32x16_bf16(a, b, c, 0, 0, 0); }
; DEV void attn_item(const Params& p, int item, char* smem) {
;     ...
;     for (int jt = 0; jt < 2; jt++) {
;       float m0 = fmaxf(fmaxf(s[jt][0], s[jt][1]), fmaxf(s[jt][2], s[jt][3]));
;       float m1 = fmaxf(fmaxf(s[jt][4], s[jt][5]), fmaxf(s[jt][6], s[jt][7]));
;       float m2 = fmaxf(fmaxf(s[jt][8], s[jt][9]), fmaxf(s[jt][10], s[jt][11]));
;       float m3 = fmaxf(fmaxf(s[jt][12], s[jt][13]), fmaxf(s[jt][14], s[jt][15]));
;       const float mx = fmaxf(fmaxf(m0, m1), fmaxf(m2, m3));
;       if (__any(mx > mrun[jt])) {
;         const float mxa = fmaxf(mx, __shfl_xor(mx, 32));
;         const float mnew = fmaxf(mrun[jt], mxa);
;         const float alpha = __builtin_amdgcn_exp2f(mrun[jt] - mnew);
;         mrun[jt] = mnew;
;         lrun[jt] *= alpha;
; #pragma unroll
;         for (int dt = 0; dt < 2; dt++)
; #pragma unroll
;           for (int r = 0; r < 16; r++) o[dt][jt][r] *= alpha;
;       }
;       const float mcur = mrun[jt];
;       float pv[16];
; #pragma unroll
;       for (int r = 0; r < 16; r++) pv[r] = __builtin_amdgcn_exp2f(s[jt][r] - mcur);
;       lrun[jt] += (((pv[0] + pv[1]) + (pv[2] + pv[3])) + ((pv[4] + pv[5]) + (pv[6] + pv[7]))) +
;                   (((pv[8] + pv[9]) + (pv[10] + pv[11])) + ((pv[12] + pv[13]) + (pv[14] + pv[15])));
;       bf16x8 pf[2];
; #pragma unroll
;       for (int ss = 0; ss < 2; ss++) {
;         uint4 u; u.x = pack2(pv[8 * ss + 0], pv[8 * ss + 1]); u.y = pack2(pv[8 * ss + 2], pv[8 * ss + 3]);
;         u.z = pack2(pv[8 * ss + 4], pv[8 * ss + 5]); u.w = pack2(pv[8 * ss + 6], pv[8 * ss + 7]);
;         pf[ss] = __builtin_bit_cast(bf16x8, u);
;       }
; #pragma unroll
;       for (int dt = 0; dt < 2; dt++)
; #pragma unroll
;         for (int ss = 0; ss < 2; ss++) {
;           uint2 lo = *(const uint2*)(Vc + (dt * 32 + c31) * VSTR + 16 * ss + 4 * hf);
;           uint2 hi = *(const uint2*)(Vc + (dt * 32 + c31) * VSTR + 16 * ss + 8 + 4 * hf);
;           uint4 u; u.x = lo.x; u.y = lo.y; u.z = hi.x; u.w = hi.y;
;           o[dt][jt] = mfma32(__builtin_bit_cast(bf16x8, u), pf[ss], o[dt][jt]);
;         }
.LBB0_755:
	v_exp_f32_e32 v0, v96
	v_exp_f32_e32 v193, v97
	v_exp_f32_e32 v194, v98
	v_mfma_f32_32x32x16_bf16 v[80:95], v[240:243], v[116:119], v[80:95]
	v_exp_f32_e32 v100, v100
	v_exp_f32_e32 v101, v101
	v_exp_f32_e32 v102, v102
	v_exp_f32_e32 v240, v103
	v_mfma_f32_32x32x16_bf16 v[80:95], v[244:247], v[120:123], v[80:95]
	v_exp_f32_e32 v103, v104
	v_exp_f32_e32 v104, v105
	v_exp_f32_e32 v105, v106
	v_exp_f32_e32 v106, v107
	v_mfma_f32_32x32x16_bf16 v[80:95], v[236:239], v[124:127], v[80:95]
	v_exp_f32_e32 v107, v108
	v_exp_f32_e32 v108, v109
	v_exp_f32_e32 v109, v110
	v_exp_f32_e32 v110, v111
	s_mulk_i32 s11, 0x1600
	v_add_u32_e32 v10, s11, v177
	v_add_u32_e32 v6, 0x3000, v10
	v_add_u32_e32 v15, 0x3800, v10
	v_exp_f32_e32 v239, v99
	ds_read2_b64 v[2:5], v6 offset0:128 offset1:130
	ds_read2_b64 v[6:9], v6 offset0:132 offset1:134
	ds_read2_b64 v[10:13], v15 offset0:224 offset1:226
	v_cvt_pk_bf16_f32 v98, v100, v101
	v_cvt_pk_bf16_f32 v96, v0, v193
	v_cvt_pk_bf16_f32 v97, v194, v239
	v_cvt_pk_bf16_f32 v99, v102, v240
	v_cvt_pk_bf16_f32 v242, v103, v104
	v_cvt_pk_bf16_f32 v243, v105, v106
	v_cvt_pk_bf16_f32 v244, v107, v108
	v_cvt_pk_bf16_f32 v245, v109, v110
	v_max3_f32 v111, v80, v81, v82
	v_max3_f32 v192, v83, v84, v85
	s_waitcnt lgkmcnt(2)
	v_mfma_f32_32x32x16_bf16 v[32:47], v[2:5], v[96:99], v[32:47]
	v_max3_f32 v236, v86, v87, v88
	v_max3_f32 v237, v89, v90, v91
	v_max3_f32 v238, v92, v93, v94
	s_waitcnt lgkmcnt(0)
	v_mfma_f32_32x32x16_bf16 v[16:31], v[10:13], v[96:99], v[16:31]
	ds_read2_b64 v[96:99], v15 offset0:228 offset1:230
	v_max3_f32 v15, v111, v192, v95
	v_max3_f32 v236, v236, v237, v238
	v_max_f32_e32 v15, v15, v236
	v_cmp_gt_f32_e32 vcc, v15, v213
	s_cbranch_vccz .LBB0_757
	v_mbcnt_hi_u32_b32 v111, -1, v215
	v_and_b32_e32 v236, 64, v111
	v_xor_b32_e32 v192, 32, v111
	v_add_u32_e32 v236, 64, v236
	v_cmp_lt_i32_e32 vcc, v192, v236
	s_nop 1
	v_cndmask_b32_e32 v111, v111, v192, vcc
	v_lshlrev_b32_e32 v111, 2, v111
	ds_bpermute_b32 v111, v111, v15
	s_waitcnt lgkmcnt(0)
	v_max_f32_e32 v111, v15, v111
	v_exp_f32_e64 v192, -v111
	v_add_f32_e32 v175, v175, v111
	v_mov_b32_e32 v213, 0x41000000
	v_sub_f32_e32 v80, v80, v111
	v_sub_f32_e32 v81, v81, v111
	v_sub_f32_e32 v82, v82, v111
	v_sub_f32_e32 v83, v83, v111
	v_sub_f32_e32 v84, v84, v111
	v_sub_f32_e32 v85, v85, v111
	v_sub_f32_e32 v86, v86, v111
	v_sub_f32_e32 v87, v87, v111
	v_sub_f32_e32 v88, v88, v111
	v_sub_f32_e32 v89, v89, v111
	v_sub_f32_e32 v90, v90, v111
	v_sub_f32_e32 v91, v91, v111
	v_sub_f32_e32 v92, v92, v111
	v_sub_f32_e32 v93, v93, v111
	v_sub_f32_e32 v94, v94, v111
	v_sub_f32_e32 v95, v95, v111
	v_sub_f32_e32 v220, v220, v111
	v_sub_f32_e32 v221, v221, v111
	v_sub_f32_e32 v222, v222, v111
	v_sub_f32_e32 v223, v223, v111
	v_sub_f32_e32 v224, v224, v111
	v_sub_f32_e32 v225, v225, v111
	v_sub_f32_e32 v226, v226, v111
	v_sub_f32_e32 v227, v227, v111
	v_sub_f32_e32 v228, v228, v111
	v_sub_f32_e32 v229, v229, v111
	v_sub_f32_e32 v230, v230, v111
	v_sub_f32_e32 v231, v231, v111
	v_sub_f32_e32 v232, v232, v111
	v_sub_f32_e32 v233, v233, v111
	v_sub_f32_e32 v234, v234, v111
	v_sub_f32_e32 v235, v235, v111
	v_mul_f32_e32 v184, v184, v192
	v_pk_mul_f32 v[78:79], v[78:79], v[192:193] op_sel_hi:[1,0]
	v_pk_mul_f32 v[76:77], v[76:77], v[192:193] op_sel_hi:[1,0]
	v_pk_mul_f32 v[74:75], v[74:75], v[192:193] op_sel_hi:[1,0]
	v_pk_mul_f32 v[72:73], v[72:73], v[192:193] op_sel_hi:[1,0]
	v_pk_mul_f32 v[70:71], v[70:71], v[192:193] op_sel_hi:[1,0]
	v_pk_mul_f32 v[68:69], v[68:69], v[192:193] op_sel_hi:[1,0]
	v_pk_mul_f32 v[66:67], v[66:67], v[192:193] op_sel_hi:[1,0]
	v_pk_mul_f32 v[64:65], v[64:65], v[192:193] op_sel_hi:[1,0]
	v_pk_mul_f32 v[62:63], v[62:63], v[192:193] op_sel_hi:[1,0]
	v_pk_mul_f32 v[60:61], v[60:61], v[192:193] op_sel_hi:[1,0]
	v_pk_mul_f32 v[58:59], v[58:59], v[192:193] op_sel_hi:[1,0]
	v_pk_mul_f32 v[56:57], v[56:57], v[192:193] op_sel_hi:[1,0]
	v_pk_mul_f32 v[54:55], v[54:55], v[192:193] op_sel_hi:[1,0]
	v_pk_mul_f32 v[52:53], v[52:53], v[192:193] op_sel_hi:[1,0]
	v_pk_mul_f32 v[50:51], v[50:51], v[192:193] op_sel_hi:[1,0]
	v_pk_mul_f32 v[48:49], v[48:49], v[192:193] op_sel_hi:[1,0]
.LBB0_757:
	v_exp_f32_e32 v80, v80
	v_exp_f32_e32 v81, v81
	v_exp_f32_e32 v82, v82
	v_mfma_f32_32x32x16_bf16 v[32:47], v[6:9], v[242:245], v[32:47]
	v_exp_f32_e32 v83, v83
	v_exp_f32_e32 v84, v84
	v_exp_f32_e32 v85, v85
	s_waitcnt lgkmcnt(0)
	v_mfma_f32_32x32x16_bf16 v[16:31], v[96:99], v[242:245], v[16:31]
	v_exp_f32_e32 v86, v86
	v_exp_f32_e32 v111, v87
	v_exp_f32_e32 v87, v88
	v_exp_f32_e32 v88, v89
	v_add_f32_e32 v0, v0, v193
	v_add_f32_e32 v236, v194, v239
	v_cvt_pk_bf16_f32 v242, v80, v81
	v_cvt_pk_bf16_f32 v243, v82, v83
	v_cvt_pk_bf16_f32 v244, v84, v85
	v_cvt_pk_bf16_f32 v245, v86, v111
	v_exp_f32_e32 v89, v90
	v_exp_f32_e32 v90, v91
	v_exp_f32_e32 v91, v92
	v_mfma_f32_32x32x16_bf16 v[64:79], v[2:5], v[242:245], v[64:79]
	v_exp_f32_e32 v92, v93
	v_exp_f32_e32 v2, v94
	v_exp_f32_e32 v3, v95
	v_add_f32_e32 v0, v0, v236
	v_add_f32_e32 v236, v100, v101
	v_mfma_f32_32x32x16_bf16 v[48:63], v[10:13], v[242:245], v[48:63]
	v_cvt_pk_bf16_f32 v246, v87, v88
	v_cvt_pk_bf16_f32 v247, v89, v90
	v_cvt_pk_bf16_f32 v248, v91, v92
	v_cvt_pk_bf16_f32 v249, v2, v3
	v_add_f32_e32 v237, v102, v240
	v_add_f32_e32 v236, v236, v237
	v_mfma_f32_32x32x16_bf16 v[64:79], v[6:9], v[246:249], v[64:79]
	s_add_i32 s12, s12, 1
	s_and_b32 s14, s12, 1
	s_mul_i32 s15, s14, 0x1a00
	v_lshlrev_b32_e32 v15, 1, v191
	v_lshlrev_b32_e32 v192, 1, v176
	v_add3_u32 v4, s15, v15, v192
	v_add_f32_e32 v0, v0, v236
	v_add_f32_e32 v236, v103, v104
	v_add_f32_e32 v237, v105, v106
	v_add_f32_e32 v236, v236, v237
	s_waitcnt vmcnt(0)
	ds_write_b128 v4, v[168:171]
	v_mfma_f32_32x32x16_bf16 v[48:63], v[96:99], v[246:249], v[48:63]
	v_add_f32_e32 v237, v107, v108
	v_add_f32_e32 v238, v109, v110
	v_add_f32_e32 v237, v237, v238
	v_add_f32_e32 v236, v236, v237
	v_add_f32_e32 v0, v0, v236
	v_add_f32_e32 v14, v14, v0
	s_and_saveexec_b64 s[8:9], s[38:39]
	s_cbranch_execz .LBB0_752
	v_lshlrev_b32_e32 v4, 1, v174
	v_add3_u32 v4, s15, v188, v4
	ds_write_b128 v4, v[164:167]
	s_branch .LBB0_752
